# mixer work lists reordered longest-first: stick-breaking units moved into the stage-0 list ahead of the 24 small differential-attention units, which now form the stage-1 list
# speedup vs baseline: 1.0059x; 1.0059x over previous
.LBB0_454:
	s_and_b64 vcc, exec, s[10:11]
	s_cbranch_vccz .LBB0_480
	s_add_i32 s76, s76, 40
	s_branch .Lmx_diff_go
.Lmx_sb_go:
	s_mov_b64 s[12:13], s[0:1]
	s_mov_b64 s[10:11], s[0:1]
	v_mov_b32_e32 v64, v214
	s_mov_b64 s[14:15], -1
	v_bfe_u32 v66, v64, 5, 1
	v_readfirstlane_b32 s4, v64
	s_cmp_lt_i32 s76, 24
	v_lshlrev_b32_e32 v200, 2, v66
	s_cbranch_scc1 .LBB0_457
	v_lshlrev_b32_e32 v192, 2, v66
	s_mov_b64 s[14:15], 0

.LBB0_519:
	s_and_b64 vcc, exec, s[10:11]
	s_cbranch_vccz .LBB0_614
	s_and_b64 vcc, exec, s[90:91]
	s_cbranch_vccnz .Lmx_diff_go
	s_cmp_lt_i32 s76, 40
	s_cbranch_scc1 .Lmx_diff_go
	s_sub_i32 s76, s76, 40
	s_branch .Lmx_sb_go
.Lmx_diff_go:
	s_add_i32 s4, s76, -16
	s_cmp_lt_i32 s76, 24
	s_cselect_b32 s25, s76, s4
	s_mul_hi_i32 s4, s25, 0x55555556
	s_lshr_b32 s10, s4, 31
	s_add_i32 s4, s4, s10
	s_mov_b64 s[10:11], s[0:1]
	s_mul_i32 s4, s4, 3
	s_load_dwordx2 s[14:15], s[10:11], 0x100
	s_mov_b64 s[10:11], s[0:1]
	s_sub_i32 s4, s25, s4
	s_lshl_b32 s4, s4, 3
	s_load_dwordx2 s[12:13], s[10:11], 0x100
	s_mov_b64 s[18:19], s[0:1]
	s_mov_b64 s[10:11], s[0:1]
	s_add_i32 s4, s4, s5
	s_load_dwordx2 s[16:17], s[10:11], 0xb0
	s_mul_hi_i32 s10, s4, 0x2aaaaaab
	s_lshr_b32 s11, s10, 31
	s_add_i32 s10, s10, s11
	s_mul_i32 s11, s10, 6
	s_sub_i32 s27, s4, s11
	v_mov_b32_e32 v0, v214
	s_movk_i32 s11, 0x81
	s_nop 0
	v_readfirstlane_b32 s4, v0
	v_cmp_gt_i32_e32 vcc, s11, v0
	s_and_saveexec_b64 s[20:21], vcc
	s_cbranch_execz .LBB0_524
	s_movk_i32 s11, 0x80
	v_cmp_ne_u32_e32 vcc, s11, v0
	v_mov_b32_e32 v1, 0xba
	s_and_saveexec_b64 s[22:23], vcc
	s_cbranch_execz .LBB0_523
	v_ashrrev_i32_e32 v1, 31, v0
	s_getpc_b64 s[28:29]
	s_add_u32 s28, s28, _ZL3T5B@rel32@lo+4
	s_addc_u32 s29, s29, _ZL3T5B@rel32@hi+12
	v_lshl_add_u64 v[2:3], s[28:29], 0, v[0:1]
	global_load_ubyte v1, v[2:3], off
	s_waitcnt vmcnt(0)
	v_mul_u32_u24_e32 v1, 6, v1
